# GEMM main-loop heads aligned to 64 bytes, plus HID sc1 stores and phase-B rewrites
# speedup vs baseline: 1.0221x; 1.0221x over previous
.LBB0_445:
	s_add_u32 s56, s62, 0xb0080
	s_addc_u32 s57, s63, 0
	s_add_u32 s62, s60, 0x100
	v_mov_b32_e32 v2, 0
	s_addc_u32 s63, s61, 0
	s_mov_b32 s84, -2
	s_waitcnt lgkmcnt(0)
	v_mov_b32_e32 v3, v2
	v_mov_b32_e32 v4, v2
	v_mov_b32_e32 v5, v2
	v_mov_b32_e32 v6, v2
	v_mov_b32_e32 v7, v2
	v_mov_b32_e32 v8, v2
	v_mov_b32_e32 v9, v2
	v_mov_b32_e32 v18, v2
	v_mov_b32_e32 v19, v2
	v_mov_b32_e32 v20, v2
	v_mov_b32_e32 v21, v2
	v_mov_b32_e32 v22, v2
	v_mov_b32_e32 v23, v2
	v_mov_b32_e32 v24, v2
	v_mov_b32_e32 v25, v2
	v_mov_b32_e32 v34, v2
	v_mov_b32_e32 v35, v2
	v_mov_b32_e32 v36, v2
	v_mov_b32_e32 v37, v2
	v_mov_b32_e32 v38, v2
	v_mov_b32_e32 v39, v2
	v_mov_b32_e32 v40, v2
	v_mov_b32_e32 v41, v2
	v_mov_b32_e32 v50, v2
	v_mov_b32_e32 v51, v2
	v_mov_b32_e32 v52, v2
	v_mov_b32_e32 v53, v2
	v_mov_b32_e32 v54, v2
	v_mov_b32_e32 v55, v2
	v_mov_b32_e32 v56, v2
	v_mov_b32_e32 v57, v2
	v_mov_b32_e32 v10, v2
	v_mov_b32_e32 v11, v2
	v_mov_b32_e32 v12, v2
	v_mov_b32_e32 v13, v2
	v_mov_b32_e32 v14, v2
	v_mov_b32_e32 v15, v2
	v_mov_b32_e32 v16, v2
	v_mov_b32_e32 v17, v2
	v_mov_b32_e32 v26, v2
	v_mov_b32_e32 v27, v2
	v_mov_b32_e32 v28, v2
	v_mov_b32_e32 v29, v2
	v_mov_b32_e32 v30, v2
	v_mov_b32_e32 v31, v2
	v_mov_b32_e32 v32, v2
	v_mov_b32_e32 v33, v2
	v_mov_b32_e32 v42, v2
	v_mov_b32_e32 v43, v2
	v_mov_b32_e32 v44, v2
	v_mov_b32_e32 v45, v2
	v_mov_b32_e32 v46, v2
	v_mov_b32_e32 v47, v2
	v_mov_b32_e32 v48, v2
	v_mov_b32_e32 v49, v2
	v_mov_b32_e32 v58, v2
	v_mov_b32_e32 v59, v2
	v_mov_b32_e32 v60, v2
	v_mov_b32_e32 v61, v2
	v_mov_b32_e32 v62, v2
	v_mov_b32_e32 v63, v2
	v_mov_b32_e32 v64, v2
	v_mov_b32_e32 v65, v2
	v_mov_b32_e32 v66, v2
	v_mov_b32_e32 v67, v2
	v_mov_b32_e32 v68, v2
	v_mov_b32_e32 v69, v2
	v_mov_b32_e32 v70, v2
	v_mov_b32_e32 v71, v2
	v_mov_b32_e32 v72, v2
	v_mov_b32_e32 v73, v2
	v_mov_b32_e32 v82, v2
	v_mov_b32_e32 v83, v2
	v_mov_b32_e32 v84, v2
	v_mov_b32_e32 v85, v2
	v_mov_b32_e32 v86, v2
	v_mov_b32_e32 v87, v2
	v_mov_b32_e32 v88, v2
	v_mov_b32_e32 v89, v2
	v_mov_b32_e32 v98, v2
	v_mov_b32_e32 v99, v2
	v_mov_b32_e32 v100, v2
	v_mov_b32_e32 v101, v2
	v_mov_b32_e32 v102, v2
	v_mov_b32_e32 v103, v2
	v_mov_b32_e32 v104, v2
	v_mov_b32_e32 v105, v2
	v_mov_b32_e32 v118, v2
	v_mov_b32_e32 v119, v2
	v_mov_b32_e32 v120, v2
	v_mov_b32_e32 v121, v2
	v_mov_b32_e32 v122, v2
	v_mov_b32_e32 v123, v2
	v_mov_b32_e32 v124, v2
	v_mov_b32_e32 v125, v2
	v_mov_b32_e32 v74, v2
	v_mov_b32_e32 v75, v2
	v_mov_b32_e32 v76, v2
	v_mov_b32_e32 v77, v2
	v_mov_b32_e32 v78, v2
	v_mov_b32_e32 v79, v2
	v_mov_b32_e32 v80, v2
	v_mov_b32_e32 v81, v2
	v_mov_b32_e32 v90, v2
	v_mov_b32_e32 v91, v2
	v_mov_b32_e32 v92, v2
	v_mov_b32_e32 v93, v2
	v_mov_b32_e32 v94, v2
	v_mov_b32_e32 v95, v2
	v_mov_b32_e32 v96, v2
	v_mov_b32_e32 v97, v2
	v_mov_b32_e32 v106, v2
	v_mov_b32_e32 v107, v2
	v_mov_b32_e32 v108, v2
	v_mov_b32_e32 v109, v2
	v_mov_b32_e32 v110, v2
	v_mov_b32_e32 v111, v2
	v_mov_b32_e32 v112, v2
	v_mov_b32_e32 v113, v2
	v_mov_b32_e32 v138, v2
	v_mov_b32_e32 v139, v2
	v_mov_b32_e32 v140, v2
	v_mov_b32_e32 v141, v2
	v_mov_b32_e32 v142, v2
	v_mov_b32_e32 v143, v2
	v_mov_b32_e32 v144, v2
	v_mov_b32_e32 v145, v2
	s_mov_b64 s[12:13], 0xb0000
	s_mov_b64 s[86:87], 0x108000
	s_mov_b64 s[96:97], 0x58080
	s_mov_b64 vcc, 0xb0080
	s_mov_b64 s[0:1], 0x108080
	.p2alignl 6, 3212836864

.LBB0_487:
	s_ashr_i32 s57, s56, 31
	s_lshl_b64 s[20:21], s[56:57], 19
	s_add_u32 s60, s94, s20
	s_addc_u32 s61, s95, s21
	s_and_b64 s[20:21], s[54:55], exec
	s_cselect_b32 s57, s61, s69
	s_cselect_b32 s86, s60, s68
	s_ashr_i32 s51, s50, 31
	s_lshl_b64 s[20:21], s[50:51], 19
	s_add_u32 s62, s15, s20
	s_addc_u32 s63, s42, s21
	s_and_b64 s[20:21], s[54:55], exec
	s_cselect_b32 s51, s63, s77
	s_cselect_b32 s87, s62, s76
	s_add_u32 s68, s68, 0x40080
	s_addc_u32 s69, s69, 0
	s_add_u32 s91, s76, 0x100
	v_mov_b32_e32 v2, 0
	s_addc_u32 s96, s77, 0
	s_mov_b32 s97, -2
	v_mov_b32_e32 v3, v2
	v_mov_b32_e32 v4, v2
	v_mov_b32_e32 v5, v2
	v_mov_b32_e32 v10, v2
	v_mov_b32_e32 v11, v2
	v_mov_b32_e32 v12, v2
	v_mov_b32_e32 v13, v2
	v_mov_b32_e32 v22, v2
	v_mov_b32_e32 v23, v2
	v_mov_b32_e32 v24, v2
	v_mov_b32_e32 v25, v2
	v_mov_b32_e32 v26, v2
	v_mov_b32_e32 v27, v2
	v_mov_b32_e32 v28, v2
	v_mov_b32_e32 v29, v2
	v_mov_b32_e32 v38, v2
	v_mov_b32_e32 v39, v2
	v_mov_b32_e32 v40, v2
	v_mov_b32_e32 v41, v2
	v_mov_b32_e32 v42, v2
	v_mov_b32_e32 v43, v2
	v_mov_b32_e32 v44, v2
	v_mov_b32_e32 v45, v2
	v_mov_b32_e32 v54, v2
	v_mov_b32_e32 v55, v2
	v_mov_b32_e32 v56, v2
	v_mov_b32_e32 v57, v2
	v_mov_b32_e32 v58, v2
	v_mov_b32_e32 v59, v2
	v_mov_b32_e32 v60, v2
	v_mov_b32_e32 v61, v2
	v_mov_b32_e32 v6, v2
	v_mov_b32_e32 v7, v2
	v_mov_b32_e32 v8, v2
	v_mov_b32_e32 v9, v2
	v_mov_b32_e32 v14, v2
	v_mov_b32_e32 v15, v2
	v_mov_b32_e32 v16, v2
	v_mov_b32_e32 v17, v2
	v_mov_b32_e32 v18, v2
	v_mov_b32_e32 v19, v2
	v_mov_b32_e32 v20, v2
	v_mov_b32_e32 v21, v2
	v_mov_b32_e32 v30, v2
	v_mov_b32_e32 v31, v2
	v_mov_b32_e32 v32, v2
	v_mov_b32_e32 v33, v2
	v_mov_b32_e32 v34, v2
	v_mov_b32_e32 v35, v2
	v_mov_b32_e32 v36, v2
	v_mov_b32_e32 v37, v2
	v_mov_b32_e32 v46, v2
	v_mov_b32_e32 v47, v2
	v_mov_b32_e32 v48, v2
	v_mov_b32_e32 v49, v2
	v_mov_b32_e32 v50, v2
	v_mov_b32_e32 v51, v2
	v_mov_b32_e32 v52, v2
	v_mov_b32_e32 v53, v2
	v_mov_b32_e32 v62, v2
	v_mov_b32_e32 v63, v2
	v_mov_b32_e32 v64, v2
	v_mov_b32_e32 v65, v2
	v_mov_b32_e32 v70, v2
	v_mov_b32_e32 v71, v2
	v_mov_b32_e32 v72, v2
	v_mov_b32_e32 v73, v2
	v_mov_b32_e32 v74, v2
	v_mov_b32_e32 v75, v2
	v_mov_b32_e32 v76, v2
	v_mov_b32_e32 v77, v2
	v_mov_b32_e32 v86, v2
	v_mov_b32_e32 v87, v2
	v_mov_b32_e32 v88, v2
	v_mov_b32_e32 v89, v2
	v_mov_b32_e32 v90, v2
	v_mov_b32_e32 v91, v2
	v_mov_b32_e32 v92, v2
	v_mov_b32_e32 v93, v2
	v_mov_b32_e32 v102, v2
	v_mov_b32_e32 v103, v2
	v_mov_b32_e32 v104, v2
	v_mov_b32_e32 v105, v2
	v_mov_b32_e32 v106, v2
	v_mov_b32_e32 v107, v2
	v_mov_b32_e32 v108, v2
	v_mov_b32_e32 v109, v2
	v_mov_b32_e32 v118, v2
	v_mov_b32_e32 v119, v2
	v_mov_b32_e32 v120, v2
	v_mov_b32_e32 v121, v2
	v_mov_b32_e32 v122, v2
	v_mov_b32_e32 v123, v2
	v_mov_b32_e32 v124, v2
	v_mov_b32_e32 v125, v2
	v_mov_b32_e32 v66, v2
	v_mov_b32_e32 v67, v2
	v_mov_b32_e32 v68, v2
	v_mov_b32_e32 v69, v2
	v_mov_b32_e32 v78, v2
	v_mov_b32_e32 v79, v2
	v_mov_b32_e32 v80, v2
	v_mov_b32_e32 v81, v2
	v_mov_b32_e32 v82, v2
	v_mov_b32_e32 v83, v2
	v_mov_b32_e32 v84, v2
	v_mov_b32_e32 v85, v2
	v_mov_b32_e32 v94, v2
	v_mov_b32_e32 v95, v2
	v_mov_b32_e32 v96, v2
	v_mov_b32_e32 v97, v2
	v_mov_b32_e32 v98, v2
	v_mov_b32_e32 v99, v2
	v_mov_b32_e32 v100, v2
	v_mov_b32_e32 v101, v2
	v_mov_b32_e32 v110, v2
	v_mov_b32_e32 v111, v2
	v_mov_b32_e32 v112, v2
	v_mov_b32_e32 v113, v2
	v_mov_b32_e32 v114, v2
	v_mov_b32_e32 v115, v2
	v_mov_b32_e32 v116, v2
	v_mov_b32_e32 v117, v2
	v_mov_b32_e32 v126, v2
	v_mov_b32_e32 v127, v2
	v_mov_b32_e32 v128, v2
	v_mov_b32_e32 v129, v2
	.p2alignl 6, 3212836864

.LBB0_561:
	s_ashr_i32 s51, s50, 31
	s_lshl_b64 s[56:57], s[50:51], 19
	s_add_u32 s56, s15, s56
	s_addc_u32 s57, s42, s57
	s_and_b64 s[60:61], s[54:55], exec
	s_cselect_b32 s51, s57, s63
	s_cselect_b32 s86, s56, s62
	s_ashr_i32 s49, s48, 31
	s_lshl_b64 s[60:61], s[48:49], 19
	s_add_u32 s60, s43, s60
	s_addc_u32 s61, s46, s61
	s_and_b64 s[76:77], s[54:55], exec
	s_cselect_b32 s49, s61, s69
	s_cselect_b32 s87, s60, s68
	s_lshl_b32 s20, s20, 11
	s_and_b32 s20, s20, 0x1800
	s_waitcnt lgkmcnt(0)
	v_mov_b32_e32 v2, v1
	v_mov_b32_e32 v3, v1
	s_add_u32 s97, s68, 0x100
	v_mov_b32_e32 v0, v1
	v_mov_b64_e32 v[6:7], v[2:3]
	v_mov_b64_e32 v[10:11], v[2:3]
	v_mov_b64_e32 v[22:23], v[2:3]
	v_mov_b64_e32 v[26:27], v[2:3]
	v_mov_b64_e32 v[38:39], v[2:3]
	v_mov_b64_e32 v[42:43], v[2:3]
	v_mov_b64_e32 v[54:55], v[2:3]
	v_mov_b64_e32 v[58:59], v[2:3]
	v_mov_b64_e32 v[14:15], v[2:3]
	v_mov_b64_e32 v[18:19], v[2:3]
	v_mov_b64_e32 v[30:31], v[2:3]
	v_mov_b64_e32 v[34:35], v[2:3]
	v_mov_b64_e32 v[46:47], v[2:3]
	v_mov_b64_e32 v[50:51], v[2:3]
	v_mov_b64_e32 v[62:63], v[2:3]
	v_mov_b64_e32 v[66:67], v[2:3]
	v_mov_b64_e32 v[70:71], v[2:3]
	v_mov_b64_e32 v[74:75], v[2:3]
	v_mov_b64_e32 v[86:87], v[2:3]
	v_mov_b64_e32 v[90:91], v[2:3]
	v_mov_b64_e32 v[102:103], v[2:3]
	v_mov_b64_e32 v[106:107], v[2:3]
	v_mov_b64_e32 v[130:131], v[2:3]
	v_mov_b64_e32 v[138:139], v[2:3]
	v_mov_b64_e32 v[78:79], v[2:3]
	v_mov_b64_e32 v[82:83], v[2:3]
	v_mov_b64_e32 v[94:95], v[2:3]
	v_mov_b64_e32 v[98:99], v[2:3]
	v_mov_b64_e32 v[110:111], v[2:3]
	v_mov_b64_e32 v[114:115], v[2:3]
	v_mov_b64_e32 v[142:143], v[2:3]
	v_mov_b64_e32 v[146:147], v[2:3]
	v_add_u32_e32 v219, s20, v216
	v_lshl_add_u64 v[116:117], s[62:63], 0, v[186:187]
	s_addc_u32 vcc_lo, s69, 0
	s_mov_b32 vcc_hi, -2
	s_mov_b64 s[68:69], 0
	v_mov_b64_e32 v[4:5], v[0:1]
	v_mov_b64_e32 v[8:9], v[0:1]
	v_mov_b64_e32 v[20:21], v[0:1]
	v_mov_b64_e32 v[24:25], v[0:1]
	v_mov_b64_e32 v[36:37], v[0:1]
	v_mov_b64_e32 v[40:41], v[0:1]
	v_mov_b64_e32 v[52:53], v[0:1]
	v_mov_b64_e32 v[56:57], v[0:1]
	v_mov_b64_e32 v[12:13], v[0:1]
	v_mov_b64_e32 v[16:17], v[0:1]
	v_mov_b64_e32 v[28:29], v[0:1]
	v_mov_b64_e32 v[32:33], v[0:1]
	v_mov_b64_e32 v[44:45], v[0:1]
	v_mov_b64_e32 v[48:49], v[0:1]
	v_mov_b64_e32 v[60:61], v[0:1]
	v_mov_b64_e32 v[64:65], v[0:1]
	v_mov_b64_e32 v[68:69], v[0:1]
	v_mov_b64_e32 v[72:73], v[0:1]
	v_mov_b64_e32 v[84:85], v[0:1]
	v_mov_b64_e32 v[88:89], v[0:1]
	v_mov_b64_e32 v[100:101], v[0:1]
	v_mov_b64_e32 v[104:105], v[0:1]
	v_mov_b64_e32 v[128:129], v[0:1]
	v_mov_b64_e32 v[136:137], v[0:1]
	v_mov_b64_e32 v[76:77], v[0:1]
	v_mov_b64_e32 v[80:81], v[0:1]
	v_mov_b64_e32 v[92:93], v[0:1]
	v_mov_b64_e32 v[96:97], v[0:1]
	v_mov_b64_e32 v[108:109], v[0:1]
	v_mov_b64_e32 v[112:113], v[0:1]
	v_mov_b64_e32 v[140:141], v[0:1]
	v_mov_b64_e32 v[144:145], v[0:1]
	s_branch .LBB0_563
	.p2alignl 6, 3212836864

.LBB0_603:
	s_ashr_i32 s51, s50, 31
	s_lshl_b64 s[20:21], s[50:51], 18
	s_add_u32 s78, s0, s20
	s_addc_u32 s79, s1, s21
	s_and_b64 s[20:21], s[56:57], exec
	s_cselect_b32 s42, s79, s7
	s_cselect_b32 s43, s78, s6
	s_ashr_i32 s49, s48, 31
	s_lshl_b64 s[20:21], s[48:49], 18
	s_add_u32 s40, s76, s20
	s_addc_u32 s41, s77, s21
	s_and_b64 s[20:21], s[56:57], exec
	s_cselect_b32 s46, s41, s69
	s_cselect_b32 s47, s40, s68
	s_add_u32 s6, s6, 0x20080
	s_addc_u32 s7, s7, 0
	s_add_u32 s49, s68, 0x100
	v_mov_b32_e32 v2, 0
	s_addc_u32 s51, s69, 0
	s_mov_b32 s84, -2
	s_waitcnt lgkmcnt(0)
	v_mov_b32_e32 v3, v2
	v_mov_b32_e32 v4, v2
	v_mov_b32_e32 v5, v2
	v_mov_b32_e32 v6, v2
	v_mov_b32_e32 v7, v2
	v_mov_b32_e32 v8, v2
	v_mov_b32_e32 v9, v2
	v_mov_b32_e32 v18, v2
	v_mov_b32_e32 v19, v2
	v_mov_b32_e32 v20, v2
	v_mov_b32_e32 v21, v2
	v_mov_b32_e32 v22, v2
	v_mov_b32_e32 v23, v2
	v_mov_b32_e32 v24, v2
	v_mov_b32_e32 v25, v2
	v_mov_b32_e32 v34, v2
	v_mov_b32_e32 v35, v2
	v_mov_b32_e32 v36, v2
	v_mov_b32_e32 v37, v2
	v_mov_b32_e32 v38, v2
	v_mov_b32_e32 v39, v2
	v_mov_b32_e32 v40, v2
	v_mov_b32_e32 v41, v2
	v_mov_b32_e32 v50, v2
	v_mov_b32_e32 v51, v2
	v_mov_b32_e32 v52, v2
	v_mov_b32_e32 v53, v2
	v_mov_b32_e32 v54, v2
	v_mov_b32_e32 v55, v2
	v_mov_b32_e32 v56, v2
	v_mov_b32_e32 v57, v2
	v_mov_b32_e32 v10, v2
	v_mov_b32_e32 v11, v2
	v_mov_b32_e32 v12, v2
	v_mov_b32_e32 v13, v2
	v_mov_b32_e32 v14, v2
	v_mov_b32_e32 v15, v2
	v_mov_b32_e32 v16, v2
	v_mov_b32_e32 v17, v2
	v_mov_b32_e32 v26, v2
	v_mov_b32_e32 v27, v2
	v_mov_b32_e32 v28, v2
	v_mov_b32_e32 v29, v2
	v_mov_b32_e32 v30, v2
	v_mov_b32_e32 v31, v2
	v_mov_b32_e32 v32, v2
	v_mov_b32_e32 v33, v2
	v_mov_b32_e32 v42, v2
	v_mov_b32_e32 v43, v2
	v_mov_b32_e32 v44, v2
	v_mov_b32_e32 v45, v2
	v_mov_b32_e32 v46, v2
	v_mov_b32_e32 v47, v2
	v_mov_b32_e32 v48, v2
	v_mov_b32_e32 v49, v2
	v_mov_b32_e32 v58, v2
	v_mov_b32_e32 v59, v2
	v_mov_b32_e32 v60, v2
	v_mov_b32_e32 v61, v2
	v_mov_b32_e32 v62, v2
	v_mov_b32_e32 v63, v2
	v_mov_b32_e32 v64, v2
	v_mov_b32_e32 v65, v2
	v_mov_b32_e32 v66, v2
	v_mov_b32_e32 v67, v2
	v_mov_b32_e32 v68, v2
	v_mov_b32_e32 v69, v2
	v_mov_b32_e32 v70, v2
	v_mov_b32_e32 v71, v2
	v_mov_b32_e32 v72, v2
	v_mov_b32_e32 v73, v2
	v_mov_b32_e32 v82, v2
	v_mov_b32_e32 v83, v2
	v_mov_b32_e32 v84, v2
	v_mov_b32_e32 v85, v2
	v_mov_b32_e32 v86, v2
	v_mov_b32_e32 v87, v2
	v_mov_b32_e32 v88, v2
	v_mov_b32_e32 v89, v2
	v_mov_b32_e32 v98, v2
	v_mov_b32_e32 v99, v2
	v_mov_b32_e32 v100, v2
	v_mov_b32_e32 v101, v2
	v_mov_b32_e32 v102, v2
	v_mov_b32_e32 v103, v2
	v_mov_b32_e32 v104, v2
	v_mov_b32_e32 v105, v2
	v_mov_b32_e32 v114, v2
	v_mov_b32_e32 v115, v2
	v_mov_b32_e32 v116, v2
	v_mov_b32_e32 v117, v2
	v_mov_b32_e32 v118, v2
	v_mov_b32_e32 v119, v2
	v_mov_b32_e32 v120, v2
	v_mov_b32_e32 v121, v2
	v_mov_b32_e32 v74, v2
	v_mov_b32_e32 v75, v2
	v_mov_b32_e32 v76, v2
	v_mov_b32_e32 v77, v2
	v_mov_b32_e32 v78, v2
	v_mov_b32_e32 v79, v2
	v_mov_b32_e32 v80, v2
	v_mov_b32_e32 v81, v2
	v_mov_b32_e32 v90, v2
	v_mov_b32_e32 v91, v2
	v_mov_b32_e32 v92, v2
	v_mov_b32_e32 v93, v2
	v_mov_b32_e32 v94, v2
	v_mov_b32_e32 v95, v2
	v_mov_b32_e32 v96, v2
	v_mov_b32_e32 v97, v2
	v_mov_b32_e32 v106, v2
	v_mov_b32_e32 v107, v2
	v_mov_b32_e32 v108, v2
	v_mov_b32_e32 v109, v2
	v_mov_b32_e32 v110, v2
	v_mov_b32_e32 v111, v2
	v_mov_b32_e32 v112, v2
	v_mov_b32_e32 v113, v2
	v_mov_b32_e32 v122, v2
	v_mov_b32_e32 v123, v2
	v_mov_b32_e32 v124, v2
	v_mov_b32_e32 v125, v2
	v_mov_b32_e32 v126, v2
	v_mov_b32_e32 v127, v2
	v_mov_b32_e32 v128, v2
	v_mov_b32_e32 v129, v2
	.p2alignl 6, 3212836864

.LBB0_777:
	s_ashr_i32 s61, s60, 31
	s_lshl_b64 s[20:21], s[60:61], 19
	s_add_u32 s62, s94, s20
	s_addc_u32 s63, s95, s21
	s_and_b64 s[20:21], s[56:57], exec
	s_cselect_b32 s61, s63, s77
	s_cselect_b32 s85, s62, s76
	s_ashr_i32 s59, s58, 31
	s_lshl_b64 s[20:21], s[58:59], 19
	s_add_u32 s68, s15, s20
	s_addc_u32 s69, s42, s21
	s_and_b64 s[20:21], s[56:57], exec
	s_cselect_b32 s59, s69, s79
	s_cselect_b32 s86, s68, s78
	s_add_u32 s76, s76, 0x40080
	s_addc_u32 s77, s77, 0
	s_add_u32 s87, s78, 0x100
	v_mov_b32_e32 v2, 0
	s_addc_u32 vcc_lo, s79, 0
	s_mov_b32 vcc_hi, -2
	s_waitcnt lgkmcnt(0)
	v_mov_b32_e32 v3, v2
	v_mov_b32_e32 v4, v2
	v_mov_b32_e32 v5, v2
	v_mov_b32_e32 v6, v2
	v_mov_b32_e32 v7, v2
	v_mov_b32_e32 v8, v2
	v_mov_b32_e32 v9, v2
	v_mov_b32_e32 v18, v2
	v_mov_b32_e32 v19, v2
	v_mov_b32_e32 v20, v2
	v_mov_b32_e32 v21, v2
	v_mov_b32_e32 v22, v2
	v_mov_b32_e32 v23, v2
	v_mov_b32_e32 v24, v2
	v_mov_b32_e32 v25, v2
	v_mov_b32_e32 v34, v2
	v_mov_b32_e32 v35, v2
	v_mov_b32_e32 v36, v2
	v_mov_b32_e32 v37, v2
	v_mov_b32_e32 v38, v2
	v_mov_b32_e32 v39, v2
	v_mov_b32_e32 v40, v2
	v_mov_b32_e32 v41, v2
	v_mov_b32_e32 v50, v2
	v_mov_b32_e32 v51, v2
	v_mov_b32_e32 v52, v2
	v_mov_b32_e32 v53, v2
	v_mov_b32_e32 v54, v2
	v_mov_b32_e32 v55, v2
	v_mov_b32_e32 v56, v2
	v_mov_b32_e32 v57, v2
	v_mov_b32_e32 v10, v2
	v_mov_b32_e32 v11, v2
	v_mov_b32_e32 v12, v2
	v_mov_b32_e32 v13, v2
	v_mov_b32_e32 v14, v2
	v_mov_b32_e32 v15, v2
	v_mov_b32_e32 v16, v2
	v_mov_b32_e32 v17, v2
	v_mov_b32_e32 v26, v2
	v_mov_b32_e32 v27, v2
	v_mov_b32_e32 v28, v2
	v_mov_b32_e32 v29, v2
	v_mov_b32_e32 v30, v2
	v_mov_b32_e32 v31, v2
	v_mov_b32_e32 v32, v2
	v_mov_b32_e32 v33, v2
	v_mov_b32_e32 v42, v2
	v_mov_b32_e32 v43, v2
	v_mov_b32_e32 v44, v2
	v_mov_b32_e32 v45, v2
	v_mov_b32_e32 v46, v2
	v_mov_b32_e32 v47, v2
	v_mov_b32_e32 v48, v2
	v_mov_b32_e32 v49, v2
	v_mov_b32_e32 v58, v2
	v_mov_b32_e32 v59, v2
	v_mov_b32_e32 v60, v2
	v_mov_b32_e32 v61, v2
	v_mov_b32_e32 v62, v2
	v_mov_b32_e32 v63, v2
	v_mov_b32_e32 v64, v2
	v_mov_b32_e32 v65, v2
	v_mov_b32_e32 v66, v2
	v_mov_b32_e32 v67, v2
	v_mov_b32_e32 v68, v2
	v_mov_b32_e32 v69, v2
	v_mov_b32_e32 v70, v2
	v_mov_b32_e32 v71, v2
	v_mov_b32_e32 v72, v2
	v_mov_b32_e32 v73, v2
	v_mov_b32_e32 v82, v2
	v_mov_b32_e32 v83, v2
	v_mov_b32_e32 v84, v2
	v_mov_b32_e32 v85, v2
	v_mov_b32_e32 v86, v2
	v_mov_b32_e32 v87, v2
	v_mov_b32_e32 v88, v2
	v_mov_b32_e32 v89, v2
	v_mov_b32_e32 v98, v2
	v_mov_b32_e32 v99, v2
	v_mov_b32_e32 v100, v2
	v_mov_b32_e32 v101, v2
	v_mov_b32_e32 v102, v2
	v_mov_b32_e32 v103, v2
	v_mov_b32_e32 v104, v2
	v_mov_b32_e32 v105, v2
	v_mov_b32_e32 v114, v2
	v_mov_b32_e32 v115, v2
	v_mov_b32_e32 v116, v2
	v_mov_b32_e32 v117, v2
	v_mov_b32_e32 v118, v2
	v_mov_b32_e32 v119, v2
	v_mov_b32_e32 v120, v2
	v_mov_b32_e32 v121, v2
	v_mov_b32_e32 v74, v2
	v_mov_b32_e32 v75, v2
	v_mov_b32_e32 v76, v2
	v_mov_b32_e32 v77, v2
	v_mov_b32_e32 v78, v2
	v_mov_b32_e32 v79, v2
	v_mov_b32_e32 v80, v2
	v_mov_b32_e32 v81, v2
	v_mov_b32_e32 v90, v2
	v_mov_b32_e32 v91, v2
	v_mov_b32_e32 v92, v2
	v_mov_b32_e32 v93, v2
	v_mov_b32_e32 v94, v2
	v_mov_b32_e32 v95, v2
	v_mov_b32_e32 v96, v2
	v_mov_b32_e32 v97, v2
	v_mov_b32_e32 v106, v2
	v_mov_b32_e32 v107, v2
	v_mov_b32_e32 v108, v2
	v_mov_b32_e32 v109, v2
	v_mov_b32_e32 v110, v2
	v_mov_b32_e32 v111, v2
	v_mov_b32_e32 v112, v2
	v_mov_b32_e32 v113, v2
	v_mov_b32_e32 v122, v2
	v_mov_b32_e32 v123, v2
	v_mov_b32_e32 v124, v2
	v_mov_b32_e32 v125, v2
	v_mov_b32_e32 v126, v2
	v_mov_b32_e32 v127, v2
	v_mov_b32_e32 v128, v2
	v_mov_b32_e32 v129, v2
	.p2alignl 6, 3212836864

.LBB0_849:
	s_ashr_i32 s79, s78, 31
	s_lshl_b64 s[20:21], s[78:79], 19
	s_add_u32 s88, s4, s20
	s_addc_u32 s89, s5, s21
	s_and_b64 s[20:21], s[54:55], exec
	s_cselect_b32 s76, s89, s57
	s_cselect_b32 s77, s88, s56
	s_ashr_i32 s69, s68, 31
	s_lshl_b64 s[20:21], s[68:69], 19
	v_readlane_b32 s12, v247, 42
	s_add_u32 s94, s12, s20
	v_readlane_b32 s12, v245, 61
	s_addc_u32 s95, s12, s21
	s_and_b64 s[20:21], s[54:55], exec
	s_cselect_b32 s69, s95, s59
	s_cselect_b32 s79, s94, s58
	s_add_u32 s56, s56, 0x40080
	s_addc_u32 s57, s57, 0
	s_add_u32 s86, s58, 0x100
	v_mov_b32_e32 v2, 0
	s_addc_u32 s87, s59, 0
	s_mov_b32 s91, -2
	v_mov_b32_e32 v3, v2
	v_mov_b32_e32 v4, v2
	v_mov_b32_e32 v5, v2
	v_mov_b32_e32 v6, v2
	v_mov_b32_e32 v7, v2
	v_mov_b32_e32 v8, v2
	v_mov_b32_e32 v9, v2
	v_mov_b32_e32 v18, v2
	v_mov_b32_e32 v19, v2
	v_mov_b32_e32 v20, v2
	v_mov_b32_e32 v21, v2
	v_mov_b32_e32 v22, v2
	v_mov_b32_e32 v23, v2
	v_mov_b32_e32 v24, v2
	v_mov_b32_e32 v25, v2
	v_mov_b32_e32 v34, v2
	v_mov_b32_e32 v35, v2
	v_mov_b32_e32 v36, v2
	v_mov_b32_e32 v37, v2
	v_mov_b32_e32 v38, v2
	v_mov_b32_e32 v39, v2
	v_mov_b32_e32 v40, v2
	v_mov_b32_e32 v41, v2
	v_mov_b32_e32 v50, v2
	v_mov_b32_e32 v51, v2
	v_mov_b32_e32 v52, v2
	v_mov_b32_e32 v53, v2
	v_mov_b32_e32 v54, v2
	v_mov_b32_e32 v55, v2
	v_mov_b32_e32 v56, v2
	v_mov_b32_e32 v57, v2
	v_mov_b32_e32 v10, v2
	v_mov_b32_e32 v11, v2
	v_mov_b32_e32 v12, v2
	v_mov_b32_e32 v13, v2
	v_mov_b32_e32 v14, v2
	v_mov_b32_e32 v15, v2
	v_mov_b32_e32 v16, v2
	v_mov_b32_e32 v17, v2
	v_mov_b32_e32 v26, v2
	v_mov_b32_e32 v27, v2
	v_mov_b32_e32 v28, v2
	v_mov_b32_e32 v29, v2
	v_mov_b32_e32 v30, v2
	v_mov_b32_e32 v31, v2
	v_mov_b32_e32 v32, v2
	v_mov_b32_e32 v33, v2
	v_mov_b32_e32 v42, v2
	v_mov_b32_e32 v43, v2
	v_mov_b32_e32 v44, v2
	v_mov_b32_e32 v45, v2
	v_mov_b32_e32 v46, v2
	v_mov_b32_e32 v47, v2
	v_mov_b32_e32 v48, v2
	v_mov_b32_e32 v49, v2
	v_mov_b32_e32 v58, v2
	v_mov_b32_e32 v59, v2
	v_mov_b32_e32 v60, v2
	v_mov_b32_e32 v61, v2
	v_mov_b32_e32 v62, v2
	v_mov_b32_e32 v63, v2
	v_mov_b32_e32 v64, v2
	v_mov_b32_e32 v65, v2
	v_mov_b32_e32 v66, v2
	v_mov_b32_e32 v67, v2
	v_mov_b32_e32 v68, v2
	v_mov_b32_e32 v69, v2
	v_mov_b32_e32 v70, v2
	v_mov_b32_e32 v71, v2
	v_mov_b32_e32 v72, v2
	v_mov_b32_e32 v73, v2
	v_mov_b32_e32 v82, v2
	v_mov_b32_e32 v83, v2
	v_mov_b32_e32 v84, v2
	v_mov_b32_e32 v85, v2
	v_mov_b32_e32 v86, v2
	v_mov_b32_e32 v87, v2
	v_mov_b32_e32 v88, v2
	v_mov_b32_e32 v89, v2
	v_mov_b32_e32 v98, v2
	v_mov_b32_e32 v99, v2
	v_mov_b32_e32 v100, v2
	v_mov_b32_e32 v101, v2
	v_mov_b32_e32 v102, v2
	v_mov_b32_e32 v103, v2
	v_mov_b32_e32 v104, v2
	v_mov_b32_e32 v105, v2
	v_mov_b32_e32 v114, v2
	v_mov_b32_e32 v115, v2
	v_mov_b32_e32 v116, v2
	v_mov_b32_e32 v117, v2
	v_mov_b32_e32 v118, v2
	v_mov_b32_e32 v119, v2
	v_mov_b32_e32 v120, v2
	v_mov_b32_e32 v121, v2
	v_mov_b32_e32 v74, v2
	v_mov_b32_e32 v75, v2
	v_mov_b32_e32 v76, v2
	v_mov_b32_e32 v77, v2
	v_mov_b32_e32 v78, v2
	v_mov_b32_e32 v79, v2
	v_mov_b32_e32 v80, v2
	v_mov_b32_e32 v81, v2
	v_mov_b32_e32 v90, v2
	v_mov_b32_e32 v91, v2
	v_mov_b32_e32 v92, v2
	v_mov_b32_e32 v93, v2
	v_mov_b32_e32 v94, v2
	v_mov_b32_e32 v95, v2
	v_mov_b32_e32 v96, v2
	v_mov_b32_e32 v97, v2
	v_mov_b32_e32 v106, v2
	v_mov_b32_e32 v107, v2
	v_mov_b32_e32 v108, v2
	v_mov_b32_e32 v109, v2
	v_mov_b32_e32 v110, v2
	v_mov_b32_e32 v111, v2
	v_mov_b32_e32 v112, v2
	v_mov_b32_e32 v113, v2
	v_mov_b32_e32 v122, v2
	v_mov_b32_e32 v123, v2
	v_mov_b32_e32 v124, v2
	v_mov_b32_e32 v125, v2
	v_mov_b32_e32 v126, v2
	v_mov_b32_e32 v127, v2
	v_mov_b32_e32 v128, v2
	v_mov_b32_e32 v129, v2
	.p2alignl 6, 3212836864

.LBB0_1051:
	s_ashr_i32 s41, s40, 31
	s_lshl_b64 s[20:21], s[40:41], 17
	s_add_u32 s50, s14, s20
	s_addc_u32 s51, s15, s21
	s_and_b64 s[20:21], s[52:53], exec
	s_cselect_b32 s41, s51, s59
	s_cselect_b32 s86, s50, s58
	s_ashr_i32 s49, s48, 31
	s_lshl_b64 s[20:21], s[48:49], 17
	s_add_u32 s54, s42, s20
	s_addc_u32 s55, s43, s21
	s_and_b64 s[20:21], s[52:53], exec
	v_mov_b32_e32 v2, 0
	s_cselect_b32 s49, s55, s57
	s_cselect_b32 s87, s54, s56
	s_mov_b64 s[68:69], 0
	s_mov_b64 s[60:61], -1
	s_mov_b64 s[62:63], 0
	v_mov_b32_e32 v3, v2
	v_mov_b32_e32 v4, v2
	v_mov_b32_e32 v5, v2
	v_mov_b32_e32 v6, v2
	v_mov_b32_e32 v7, v2
	v_mov_b32_e32 v8, v2
	v_mov_b32_e32 v9, v2
	v_mov_b32_e32 v10, v2
	v_mov_b32_e32 v11, v2
	v_mov_b32_e32 v12, v2
	v_mov_b32_e32 v13, v2
	v_mov_b32_e32 v18, v2
	v_mov_b32_e32 v19, v2
	v_mov_b32_e32 v20, v2
	v_mov_b32_e32 v21, v2
	v_mov_b32_e32 v26, v2
	v_mov_b32_e32 v27, v2
	v_mov_b32_e32 v28, v2
	v_mov_b32_e32 v29, v2
	v_mov_b32_e32 v34, v2
	v_mov_b32_e32 v35, v2
	v_mov_b32_e32 v36, v2
	v_mov_b32_e32 v37, v2
	v_mov_b32_e32 v42, v2
	v_mov_b32_e32 v43, v2
	v_mov_b32_e32 v44, v2
	v_mov_b32_e32 v45, v2
	v_mov_b32_e32 v50, v2
	v_mov_b32_e32 v51, v2
	v_mov_b32_e32 v52, v2
	v_mov_b32_e32 v53, v2
	v_mov_b32_e32 v14, v2
	v_mov_b32_e32 v15, v2
	v_mov_b32_e32 v16, v2
	v_mov_b32_e32 v17, v2
	v_mov_b32_e32 v22, v2
	v_mov_b32_e32 v23, v2
	v_mov_b32_e32 v24, v2
	v_mov_b32_e32 v25, v2
	v_mov_b32_e32 v30, v2
	v_mov_b32_e32 v31, v2
	v_mov_b32_e32 v32, v2
	v_mov_b32_e32 v33, v2
	v_mov_b32_e32 v38, v2
	v_mov_b32_e32 v39, v2
	v_mov_b32_e32 v40, v2
	v_mov_b32_e32 v41, v2
	v_mov_b32_e32 v46, v2
	v_mov_b32_e32 v47, v2
	v_mov_b32_e32 v48, v2
	v_mov_b32_e32 v49, v2
	v_mov_b32_e32 v54, v2
	v_mov_b32_e32 v55, v2
	v_mov_b32_e32 v56, v2
	v_mov_b32_e32 v57, v2
	v_mov_b32_e32 v58, v2
	v_mov_b32_e32 v59, v2
	v_mov_b32_e32 v60, v2
	v_mov_b32_e32 v61, v2
	v_mov_b32_e32 v62, v2
	v_mov_b32_e32 v63, v2
	v_mov_b32_e32 v64, v2
	v_mov_b32_e32 v65, v2
	v_mov_b32_e32 v66, v2
	v_mov_b32_e32 v67, v2
	v_mov_b32_e32 v68, v2
	v_mov_b32_e32 v69, v2
	v_mov_b32_e32 v70, v2
	v_mov_b32_e32 v71, v2
	v_mov_b32_e32 v72, v2
	v_mov_b32_e32 v73, v2
	v_mov_b32_e32 v74, v2
	v_mov_b32_e32 v75, v2
	v_mov_b32_e32 v76, v2
	v_mov_b32_e32 v77, v2
	v_mov_b32_e32 v82, v2
	v_mov_b32_e32 v83, v2
	v_mov_b32_e32 v84, v2
	v_mov_b32_e32 v85, v2
	v_mov_b32_e32 v90, v2
	v_mov_b32_e32 v91, v2
	v_mov_b32_e32 v92, v2
	v_mov_b32_e32 v93, v2
	v_mov_b32_e32 v98, v2
	v_mov_b32_e32 v99, v2
	v_mov_b32_e32 v100, v2
	v_mov_b32_e32 v101, v2
	v_mov_b32_e32 v106, v2
	v_mov_b32_e32 v107, v2
	v_mov_b32_e32 v108, v2
	v_mov_b32_e32 v109, v2
	v_mov_b32_e32 v114, v2
	v_mov_b32_e32 v115, v2
	v_mov_b32_e32 v116, v2
	v_mov_b32_e32 v117, v2
	v_mov_b32_e32 v78, v2
	v_mov_b32_e32 v79, v2
	v_mov_b32_e32 v80, v2
	v_mov_b32_e32 v81, v2
	v_mov_b32_e32 v86, v2
	v_mov_b32_e32 v87, v2
	v_mov_b32_e32 v88, v2
	v_mov_b32_e32 v89, v2
	v_mov_b32_e32 v94, v2
	v_mov_b32_e32 v95, v2
	v_mov_b32_e32 v96, v2
	v_mov_b32_e32 v97, v2
	v_mov_b32_e32 v102, v2
	v_mov_b32_e32 v103, v2
	v_mov_b32_e32 v104, v2
	v_mov_b32_e32 v105, v2
	v_mov_b32_e32 v110, v2
	v_mov_b32_e32 v111, v2
	v_mov_b32_e32 v112, v2
	v_mov_b32_e32 v113, v2
	v_mov_b32_e32 v118, v2
	v_mov_b32_e32 v119, v2
	v_mov_b32_e32 v120, v2
	v_mov_b32_e32 v121, v2
	v_mov_b32_e32 v122, v2
	v_mov_b32_e32 v123, v2
	v_mov_b32_e32 v124, v2
	v_mov_b32_e32 v125, v2
	v_mov_b32_e32 v126, v2
	v_mov_b32_e32 v127, v2
	v_mov_b32_e32 v128, v2
	v_mov_b32_e32 v129, v2
	.p2alignl 6, 3212836864
